# software-pipelined cache_convert loop (prefetch next K/V rows, counted vmcnt) on top of deferred transposes
# baseline (speedup 1.0000x reference)
; DI unsigned pk2(float lo, float hi) { unsigned r; asm volatile("v_cvt_pk_bf16_f32 %0, %1, %2" : "=v"(r) : "v"(lo), "v"(hi)); return r; }
; DI unsigned short f2bf(float f) { return (unsigned short)(pk2(f, 0.f) & 0xffffu); }
; DI size_t kf_index(int seqh, int nkt, int key, int d) { return ((((size_t)seqh * nkt + (key >> 5)) * 8 + (d >> 4)) * 64 + ((key & 31) + 32 * ((d >> 3) & 1))) * 8 + (d & 7); }
; DI void cache_convert(const Prm& p, int gtid, int GT) {
;     for (size_t i = (size_t)gtid; i < (size_t)8 * 1024 * 256; i += (size_t)GT) {
;         const size_t row = i >> 8; const int c4 = (int)(i & 255) * 4, b = (int)(row >> 10), pos = (int)(row & 1023), h = c4 >> 7, d = c4 & 127;
;         const f32x4 k = *(const f32x4*)(p.cache_k + row * 1024 + c4); u32x2 o; o.x = pk2(k.x, k.y); o.y = pk2(k.z, k.w);
;         *(u32x2*)(p.KS + kf_index(b * 8 + h, 34, pos, d)) = o;
;         const f32x4 v = *(const f32x4*)(p.cache_v + row * 1024 + c4); bf16_t* vt = p.VTS + vf_index(b * 8 + h, 34, pos, d);
;         vt[0] = f2bf(v.x); vt[8] = f2bf(v.y); vt[16] = f2bf(v.z); vt[24] = f2bf(v.w); }
; }
.LBB0_2043:
	s_cmp_lt_u32 s84, 36
	s_cbranch_scc1 .LBB0_2048
	v_add_u32_e32 v0, 0xffffb800, v162
	s_mov_b32 s0, 0x200000
	v_cmp_gt_u32_e32 vcc, s0, v0
	s_and_saveexec_b64 s[0:1], vcc
	v_readlane_b32 s12, v254, 0
	v_readlane_b32 s14, v254, 2
	v_readlane_b32 s15, v254, 3
	v_readlane_b32 s18, v254, 6
	v_readlane_b32 s19, v254, 7
	v_readlane_b32 s13, v254, 1
	v_readlane_b32 s16, v254, 4
	v_readlane_b32 s17, v254, 5
	s_cbranch_execz .LBB0_2047
	s_add_i32 s8, s40, 0xffffb800
	v_mov_b32_e32 v1, 0
	s_lshl_b32 s2, s88, 11
	s_ashr_i32 s9, s8, 31
	v_lshlrev_b32_e32 v4, 2, v0
	s_add_i32 s2, s2, 0xfffee000
	s_mov_b64 s[10:11], 0
	s_mov_b64 s[12:13], 0x1fffff
	v_mov_b64_e32 v[2:3], v[0:1]
	v_lshlrev_b64 v[20:21], 4, v[2:3]
	s_lshl_b64 s[4:5], s[8:9], 4
	v_lshl_add_u64 v[22:23], s[48:49], 0, v[20:21]
	v_lshl_add_u64 v[20:21], s[46:47], 0, v[20:21]
	global_load_dwordx4 v[24:27], v[20:21], off
	global_load_dwordx4 v[28:31], v[22:23], off
	s_waitcnt vmcnt(0)
.Lcc_loop:
	v_cvt_pk_bf16_f32 v32, v24, v25
	v_cvt_pk_bf16_f32 v33, v26, v27
	v_cvt_pk_bf16_f32 v34, v28, v1
	v_cvt_pk_bf16_f32 v35, v29, v1
	v_cvt_pk_bf16_f32 v36, v30, v1
	v_cvt_pk_bf16_f32 v37, v31, v1
	v_lshl_add_u64 v[38:39], v[2:3], 0, s[8:9]
	s_mov_b64 s[6:7], exec
	v_cmp_lt_u64_e32 vcc, s[12:13], v[38:39]
	v_lshl_add_u64 v[20:21], v[20:21], 0, s[4:5]
	v_lshl_add_u64 v[22:23], v[22:23], 0, s[4:5]
	s_nop 1
	s_or_b64 s[10:11], vcc, s[10:11]
	s_andn2_b64 exec, exec, s[10:11]
	s_cbranch_execz .Lcc_nopf
	global_load_dwordx4 v[24:27], v[20:21], off
	global_load_dwordx4 v[28:31], v[22:23], off
.Lcc_nopf:
	s_mov_b64 exec, s[6:7]
	v_alignbit_b32 v5, v3, v2, 8
	v_bfe_u32 v12, v4, 7, 3
	v_lshrrev_b32_e32 v16, 15, v2
	v_and_b32_e32 v14, 0x7c, v4
	v_and_or_b32 v12, v16, 56, v12
	v_bfe_u32 v16, v5, 5, 5
	v_and_b32_e32 v17, 4, v4
	v_lshlrev_b32_e32 v18, 2, v14
	v_and_b32_e32 v19, 31, v5
	v_mad_u32_u24 v16, v12, 34, v16
	v_lshlrev_b32_e32 v14, 1, v17
	v_and_b32_e32 v12, 0x1c0, v18
	v_and_or_b32 v17, v18, 32, v19
	v_lshlrev_b32_e32 v18, 9, v16
	v_mov_b32_e32 v13, v1
	v_or3_b32 v12, v18, v12, v17
	v_mov_b32_e32 v15, v1
	v_lshl_add_u64 v[12:13], v[12:13], 4, s[14:15]
	v_lshl_add_u64 v[12:13], v[12:13], 0, v[14:15]
	global_store_dwordx2 v[12:13], v[32:33], off
	v_lshrrev_b32_e32 v0, 10, v2
	v_and_b32_e32 v11, 28, v4
	v_lshlrev_b32_e32 v13, 3, v5
	v_bfe_u32 v10, v4, 5, 2
	v_and_b32_e32 v0, 4, v0
	v_and_or_b32 v13, v13, 32, v11
	v_lshlrev_b32_e32 v11, 3, v16
	v_or3_b32 v0, v11, v0, v10
	v_lshlrev_b64 v[10:11], 10, v[0:1]
	v_lshlrev_b32_e32 v0, 4, v13
	v_lshl_add_u64 v[10:11], s[18:19], 0, v[10:11]
	v_lshrrev_b32_e32 v12, 7, v2
	v_lshl_add_u64 v[10:11], v[10:11], 0, v[0:1]
	v_and_b32_e32 v0, 8, v5
	v_lshl_add_u64 v[10:11], v[10:11], 0, v[0:1]
	v_and_b32_e32 v0, 6, v12
	v_lshl_add_u64 v[10:11], v[10:11], 0, v[0:1]
	global_store_short v[10:11], v34, off
	global_store_short v[10:11], v35, off offset:16
	global_store_short v[10:11], v36, off offset:32
	global_store_short v[10:11], v37, off offset:48
	v_mov_b32_e32 v2, v38
	v_mov_b32_e32 v3, v39
	v_add_u32_e32 v4, s2, v4
	s_waitcnt vmcnt(5)
	s_andn2_b64 exec, exec, s[10:11]
	s_cbranch_execnz .Lcc_loop
